# P2 row-major output loop software-pipelined: 8 LDS reads in flight with counted lgkmcnt instead of one LDS round trip per store
# baseline (speedup 1.0000x reference)
.LBB0_277:
	v_mov_b32_e32 v0, v8
	ds_read_b128 v[16:19], v0
	ds_read_b128 v[20:23], v0 offset:8448
	v_add_u32_e32 v0, 0x4200, v8
	ds_read_b128 v[24:27], v0
	ds_read_b128 v[28:31], v0 offset:8448
	v_add_u32_e32 v0, 0x8400, v8
	ds_read_b128 v[32:35], v0
	ds_read_b128 v[36:39], v0 offset:8448
	v_add_u32_e32 v0, 0xc600, v8
	ds_read_b128 v[40:43], v0
	ds_read_b128 v[44:47], v0 offset:8448
	s_waitcnt lgkmcnt(7)
	v_lshl_add_u64 v[14:15], v[4:5], 0, v[6:7]
	global_store_dwordx4 v[14:15], v[16:19], off
	v_add_u32_e32 v0, 0x10800, v8
	ds_read_b128 v[48:51], v0
	s_waitcnt lgkmcnt(7)
	v_lshl_add_u64 v[14:15], v[4:5], 0, v[2:3]
	global_store_dwordx4 v[14:15], v[20:23], off
	v_lshl_add_u64 v[4:5], v[4:5], 0, s[4:5]
	ds_read_b128 v[52:55], v0 offset:8448
	s_waitcnt lgkmcnt(7)
	v_lshl_add_u64 v[14:15], v[4:5], 0, v[6:7]
	global_store_dwordx4 v[14:15], v[24:27], off
	v_add_u32_e32 v0, 0x14a00, v8
	ds_read_b128 v[56:59], v0
	s_waitcnt lgkmcnt(7)
	v_lshl_add_u64 v[14:15], v[4:5], 0, v[2:3]
	global_store_dwordx4 v[14:15], v[28:31], off
	v_lshl_add_u64 v[4:5], v[4:5], 0, s[4:5]
	ds_read_b128 v[60:63], v0 offset:8448
	s_waitcnt lgkmcnt(7)
	v_lshl_add_u64 v[14:15], v[4:5], 0, v[6:7]
	global_store_dwordx4 v[14:15], v[32:35], off
	v_add_u32_e32 v0, 0x18c00, v8
	ds_read_b128 v[64:67], v0
	s_waitcnt lgkmcnt(7)
	v_lshl_add_u64 v[14:15], v[4:5], 0, v[2:3]
	global_store_dwordx4 v[14:15], v[36:39], off
	v_lshl_add_u64 v[4:5], v[4:5], 0, s[4:5]
	ds_read_b128 v[68:71], v0 offset:8448
	s_waitcnt lgkmcnt(7)
	v_lshl_add_u64 v[14:15], v[4:5], 0, v[6:7]
	global_store_dwordx4 v[14:15], v[40:43], off
	v_add_u32_e32 v0, 0x1ce00, v8
	ds_read_b128 v[72:75], v0
	s_waitcnt lgkmcnt(7)
	v_lshl_add_u64 v[14:15], v[4:5], 0, v[2:3]
	global_store_dwordx4 v[14:15], v[44:47], off
	v_lshl_add_u64 v[4:5], v[4:5], 0, s[4:5]
	ds_read_b128 v[76:79], v0 offset:8448
	s_waitcnt lgkmcnt(7)
	v_lshl_add_u64 v[14:15], v[4:5], 0, v[6:7]
	global_store_dwordx4 v[14:15], v[48:51], off
	s_waitcnt lgkmcnt(6)
	v_lshl_add_u64 v[14:15], v[4:5], 0, v[2:3]
	global_store_dwordx4 v[14:15], v[52:55], off
	v_lshl_add_u64 v[4:5], v[4:5], 0, s[4:5]
	s_waitcnt lgkmcnt(5)
	v_lshl_add_u64 v[14:15], v[4:5], 0, v[6:7]
	global_store_dwordx4 v[14:15], v[56:59], off
	s_waitcnt lgkmcnt(4)
	v_lshl_add_u64 v[14:15], v[4:5], 0, v[2:3]
	global_store_dwordx4 v[14:15], v[60:63], off
	v_lshl_add_u64 v[4:5], v[4:5], 0, s[4:5]
	s_waitcnt lgkmcnt(3)
	v_lshl_add_u64 v[14:15], v[4:5], 0, v[6:7]
	global_store_dwordx4 v[14:15], v[64:67], off
	s_waitcnt lgkmcnt(2)
	v_lshl_add_u64 v[14:15], v[4:5], 0, v[2:3]
	global_store_dwordx4 v[14:15], v[68:71], off
	v_lshl_add_u64 v[4:5], v[4:5], 0, s[4:5]
	s_waitcnt lgkmcnt(1)
	v_lshl_add_u64 v[14:15], v[4:5], 0, v[6:7]
	global_store_dwordx4 v[14:15], v[72:75], off
	s_waitcnt lgkmcnt(0)
	v_lshl_add_u64 v[14:15], v[4:5], 0, v[2:3]
	global_store_dwordx4 v[14:15], v[76:79], off
	v_lshl_add_u64 v[4:5], v[4:5], 0, s[4:5]
	s_mov_b32 s11, 0x21000
